# attention key loop starts at the first tile that can hold a nonzero softmax probability (Cauchy-Schwarz bound from per-head max q/k norms, computed in a new pass)
# speedup vs baseline: 1.0431x; 1.0431x over previous
; __device__ void attn_item(const Params& p, int s_idx, char* smem) {
;     const int qb = 63 - (s_idx >> 5), bh = s_idx & 31, b = bh >> 3, h = bh & 7;
;     const int tid = get_tid(), lane = tid & 63, wid = tid >> 6, ql = lane & 31, hh = lane >> 5;
;     const int qrow = qb * 128 + wid * 32 + ql;
;     const bf16_t* projb = p.proj + (size_t)b * S * NIN;
;     bf16x8 qf[4];
; #pragma unroll
;     for (int kk = 0; kk < 4; ++kk) qf[kk] = *(const bf16x8*)(projb + (size_t)qrow * NIN + h * 64 + kk * 16 + hh * 8);
;     f32x16 O0, O1;
; #pragma unroll
;     for (int i = 0; i < 16; ++i) { O0[i] = 0.f; O1[i] = 0.f; }
;     float mrun = -INFINITY, lsum = 0.f;
;     const int nkt = qb * 2 + 2;
;     const int wave_last = (qb * 128 + wid * 32 + 31) >> 6;
;     const int wave_q0 = qb * 128 + wid * 32;
;     const float sc = 0.125f * LOG2E;
;     struct KV { u32x4 rk[2], rv[2]; float rkb; };
;     KV sa;
;     auto gload = [&](int kt, KV& st) {
; #pragma unroll
;         for (int i = 0; i < 2; ++i) {
;             const int c = tid + 256 * i, key = c >> 3, dc = c & 7;
;             const bf16_t* src = projb + (size_t)(kt * 64 + key) * NIN + h * 64 + dc * 8;
;             st.rk[i] = *(const u32x4*)(src + 512);
;             const int keyv = c & 63, dcv = c >> 6;
;             st.rv[i] = *(const u32x4*)(projb + (size_t)(kt * 64 + keyv) * NIN + 1024 + h * 64 + dcv * 8);
;         }
;         st.rkb = p.kb[(size_t)bh * S + kt * 64 + (tid & 63)];
;     };
;     auto sstore = [&](int buf, const KV& st) {
;         bf16_t* sK = (bf16_t*)(smem + buf * ATT_BUF); bf16_t* sVt = sK + 64 * 72; float* sKb = (float*)(smem + buf * ATT_BUF + 18432);
; #pragma unroll
;         for (int i = 0; i < 2; ++i) {
;             const int c = tid + 256 * i, key = c >> 3, dc = c & 7;
;             *(u32x4*)(sK + key * 72 + dc * 8) = st.rk[i];
;             const unsigned w0 = st.rv[i].x, w1 = st.rv[i].y, w2 = st.rv[i].z, w3 = st.rv[i].w;
;             bf16_t* d = sVt + ((c >> 6) * 8) * 72 + (c & 63);
;             d[0 * 72] = (bf16_t)(w0 & 0xffffu); d[1 * 72] = (bf16_t)(w0 >> 16);
;             d[2 * 72] = (bf16_t)(w1 & 0xffffu); d[3 * 72] = (bf16_t)(w1 >> 16);
;             d[4 * 72] = (bf16_t)(w2 & 0xffffu); d[5 * 72] = (bf16_t)(w2 >> 16);
;             d[6 * 72] = (bf16_t)(w3 & 0xffffu); d[7 * 72] = (bf16_t)(w3 >> 16);
;         }
;         if (tid < 64) sKb[tid] = st.rkb;
.LBB0_107:
	s_ashr_i32 s12, s15, 5
	s_lshl_b32 s13, s15, 10
	s_sub_i32 s14, 63, s12
	v_mov_b32_e32 v3, v126
	s_and_b32 s13, s13, 0x6000
	s_and_b32 s18, s15, 31
	s_lshl_b32 s12, s14, 7
	v_ashrrev_i32_e32 v143, 6, v3
	s_mul_i32 s16, s13, 0x1410
	v_lshlrev_b32_e32 v96, 5, v143
	s_add_u32 s34, s90, s16
	v_and_b32_e32 v2, 31, v3
	v_add_u32_e32 v144, s12, v96
	s_addc_u32 s35, s91, 0
	s_lshl_b32 s15, s15, 6
	v_or_b32_e32 v98, v144, v2
	s_waitcnt lgkmcnt(0)
	v_mov_b64_e32 v[0:1], s[34:35]
	s_and_b32 s15, s15, 0x1c0
	v_bfe_u32 v4, v3, 5, 1
	v_mad_i64_i32 v[6:7], s[16:17], v98, s29, v[0:1]
	s_lshl_b32 s22, s15, 1
	s_mov_b32 s23, s21
	v_lshl_add_u64 v[6:7], v[6:7], 0, s[22:23]
	v_lshlrev_b32_e32 v112, 4, v4
	v_lshl_add_u64 v[6:7], v[6:7], 0, v[112:113]
	v_ashrrev_i32_e32 v145, 3, v3
	v_lshlrev_b32_e32 v5, 3, v3
	global_load_dwordx4 v[64:67], v[6:7], off
	global_load_dwordx4 v[68:71], v[6:7], off offset:32
	global_load_dwordx4 v[72:75], v[6:7], off offset:64
	global_load_dwordx4 v[76:79], v[6:7], off offset:96
	v_readlane_b32 s98, v165, 2
	v_readlane_b32 s99, v165, 3
	v_readlane_b32 s32, v167, 36
	v_and_b32_e32 v32, 7, v130
	v_bfe_u32 v33, v130, 3, 1
	v_lshlrev_b32_e32 v32, 7, v32
	s_mul_i32 s32, s32, 0xc00
	v_lshl_or_b32 v32, v33, 10, v32
	v_mov_b32_e32 v33, s18
	s_add_i32 s32, s32, 32
	v_and_b32_e32 v33, 7, v33
	v_add_u32_e32 v32, s32, v32
	v_lshl_add_u32 v32, v33, 2, v32
	global_load_dword v34, v32, s[98:99] sc0 sc1
	s_lshl_b32 s32, s18, 15
	v_lshlrev_b32_e32 v35, 8, v130
	v_add_u32_e32 v35, s32, v35
	v_add_u32_e32 v38, 0x4000, v35
	s_lshl_b32 s32, s14, 9
	v_add_u32_e32 v39, s32, v35
	v_lshlrev_b32_e32 v33, 8, v130
	v_sub_u32_e32 v39, v39, v33
	v_readlane_b32 s98, v165, 40
	v_readlane_b32 s99, v165, 41
	s_nop 4
	s_nop 0
	global_load_dword v36, v35, s[98:99] offset:252
	global_load_dword v37, v38, s[98:99] offset:252
	global_load_dword v39, v39, s[98:99]
	s_waitcnt vmcnt(3)
	v_max_u32_dpp v34, v34, v34 quad_perm:[1,0,3,2] row_mask:0xf bank_mask:0xf
	s_nop 1
	v_max_u32_dpp v34, v34, v34 quad_perm:[2,3,0,1] row_mask:0xf bank_mask:0xf
	s_nop 1
	v_max_u32_dpp v34, v34, v34 row_half_mirror row_mask:0xf bank_mask:0xf
	s_waitcnt vmcnt(0)
	s_nop 0
	v_readlane_b32 s98, v34, 0
	v_readlane_b32 s99, v34, 8
	v_mov_b32_e32 v41, 0xbeb908c8
	s_nop 0
	v_mov_b32_e32 v40, s98
	v_mul_f32_e32 v40, s99, v40
	v_sqrt_f32_e32 v40, v40
	s_nop 0
	v_fma_f32 v40, v40, v41, v39
	v_add_f32_e32 v40, 0xc31b0000, v40
	v_cmp_lt_f32_e32 vcc, v36, v40
	s_bcnt1_i32_b64 s32, vcc
	v_cmp_lt_f32_e32 vcc, v37, v40
	s_bcnt1_i32_b64 s98, vcc
	s_add_i32 s32, s32, s98
	s_lshl_b32 s98, s14, 1
	s_min_i32 s32, s32, s98
	s_and_b32 s32, s32, -2
	s_lshl_b32 s98, s32, 6
	s_mul_i32 s99, s98, 0x1410
	s_add_u32 s34, s34, s99
	s_addc_u32 s35, s35, 0
	v_subrev_u32_e32 v98, s98, v98
	v_subrev_u32_e32 v144, s98, v144
	v_mov_b64_e32 v[0:1], s[34:35]
	v_mad_i64_i32 v[6:7], s[16:17], v145, s29, v[0:1]
	v_and_b32_e32 v5, 56, v5
	v_lshl_add_u64 v[6:7], v[6:7], 0, s[22:23]
	v_lshlrev_b32_e32 v112, 1, v5
	v_lshl_add_u64 v[6:7], v[6:7], 0, v[112:113]
	global_load_dwordx4 v[6:9], v[6:7], off offset:1024
	v_add_u32_e32 v5, 0x100, v3
	v_and_b32_e32 v114, 63, v3
	v_ashrrev_i32_e32 v146, 3, v5
	v_mul_u32_u24_e32 v10, 0x1410, v114
	v_mov_b32_e32 v11, v113
	v_mad_i64_i32 v[0:1], s[16:17], v146, s29, v[0:1]
	v_readlane_b32 s48, v165, 26
	v_lshl_add_u64 v[10:11], s[34:35], 0, v[10:11]
	v_and_b32_e32 v100, -8, v145
	v_lshl_add_u64 v[0:1], v[0:1], 0, s[22:23]
	v_and_b32_e32 v102, -8, v146
	s_lshl_b32 s15, s18, 15
	v_readlane_b32 s62, v165, 40
	v_lshl_add_u64 v[14:15], v[10:11], 0, s[22:23]
	v_ashrrev_i32_e32 v101, 31, v100
	v_lshl_add_u64 v[0:1], v[0:1], 0, v[112:113]
	v_ashrrev_i32_e32 v103, 31, v102
	v_readlane_b32 s63, v165, 41
	s_add_u32 s16, s62, s15
	v_lshl_add_u64 v[16:17], v[100:101], 1, v[14:15]
	global_load_dwordx4 v[10:13], v[0:1], off offset:1024
	v_lshl_add_u64 v[0:1], v[102:103], 1, v[14:15]
	s_addc_u32 s17, s63, 0
	s_lshl_b32 s99, s98, 2
	s_add_u32 s16, s16, s99
	s_addc_u32 s17, s17, 0
	v_lshlrev_b32_e32 v14, 2, v114
	v_mov_b32_e32 v15, v113
	s_movk_i32 s15, 0x90
	v_lshl_add_u64 v[104:105], s[16:17], 0, v[14:15]
	v_mad_u64_u32 v[106:107], s[16:17], v145, s15, v[112:113]
	v_mul_lo_u32 v5, v100, s15
	v_lshlrev_b32_e32 v14, 1, v114
	v_or_b32_e32 v107, v5, v14
	v_mad_u64_u32 v[108:109], s[16:17], v146, s15, v[112:113]
	v_mul_lo_u32 v5, v102, s15
	s_movk_i32 s44, 0x90
	v_or_b32_e32 v109, v5, v14
	v_cmp_gt_i32_e64 s[40:41], 64, v3
	v_lshlrev_b32_e32 v147, 2, v3
	v_readlane_b32 s49, v165, 27
	v_readlane_b32 s50, v165, 28
	v_readlane_b32 s51, v165, 29
	v_readlane_b32 s52, v165, 30
	v_readlane_b32 s53, v165, 31
	v_readlane_b32 s54, v165, 32
	v_readlane_b32 s55, v165, 33
	v_readlane_b32 s56, v165, 34
	v_readlane_b32 s57, v165, 35
	v_readlane_b32 s58, v165, 36
	v_readlane_b32 s59, v165, 37
	v_readlane_b32 s60, v165, 38
	v_readlane_b32 s61, v165, 39
	s_waitcnt vmcnt(1)
	ds_write_b128 v106, v[6:9]
	global_load_dwordx4 v[6:9], v[16:17], off offset:2048
	s_waitcnt vmcnt(0)
	ds_write_b16 v107, v6 offset:9216
	ds_write_b16_d16_hi v107, v6 offset:9360
	ds_write_b16 v107, v7 offset:9504
	ds_write_b16_d16_hi v107, v7 offset:9648
	ds_write_b16 v107, v8 offset:9792
	ds_write_b16_d16_hi v107, v8 offset:9936
	ds_write_b16 v107, v9 offset:10080
	ds_write_b16_d16_hi v107, v9 offset:10224
	global_load_dwordx4 v[6:9], v[0:1], off offset:2048
	ds_write_b128 v108, v[10:13]
	s_waitcnt vmcnt(0)
	ds_write_b16 v109, v6 offset:9216
	ds_write_b16_d16_hi v109, v6 offset:9360
	ds_write_b16 v109, v7 offset:9504
	ds_write_b16_d16_hi v109, v7 offset:9648
	ds_write_b16 v109, v8 offset:9792
	ds_write_b16_d16_hi v109, v8 offset:9936
	ds_write_b16 v109, v9 offset:10080
	ds_write_b16_d16_hi v109, v9 offset:10224
	s_and_saveexec_b64 s[24:25], s[40:41]
	s_cbranch_execz .LBB0_109
	global_load_dword v0, v[104:105], off
	s_waitcnt vmcnt(0)
	ds_write_b32 v147, v0 offset:18432
; __device__ void attn_item(const Params& p, int s_idx, char* smem) {
;     ...
;     f32x16 O0, O1;
; #pragma unroll
;     for (int i = 0; i < 16; ++i) { O0[i] = 0.f; O1[i] = 0.f; }
;     float mrun = -INFINITY, lsum = 0.f;
;     const int nkt = qb * 2 + 2;
;     const int wave_last = (qb * 128 + wid * 32 + 31) >> 6;
;     const int wave_q0 = qb * 128 + wid * 32;
;     ...
;     const int pr = (ql & 0x13) | ((ql & 4) << 1) | ((ql & 8) >> 1);
.LBB0_109:
	s_or_b64 exec, exec, s[24:25]
	v_and_b32_e32 v0, 19, v3
	v_lshlrev_b32_e32 v1, 1, v2
	v_lshrrev_b32_e32 v3, 1, v3
	v_and_b32_e32 v1, 8, v1
	v_and_b32_e32 v3, 4, v3
	v_lshlrev_b32_e32 v141, 3, v4
	s_lshl_b32 s14, s14, 1
	v_or3_b32 v0, v3, v0, v1
	s_add_u32 s34, s34, s22
	v_mul_u32_u24_e32 v0, 0x48, v0
	v_lshlrev_b32_e32 v1, 1, v141
	v_mul_u32_u24_e32 v148, 0x48, v2
	v_mov_b32_e32 v14, v113
	v_mov_b32_e32 v15, v113
	s_addc_u32 s35, s35, 0
	v_lshl_add_u32 v150, v0, 1, v1
	v_lshl_add_u32 v152, v148, 1, v1
	s_mov_b32 s20, 0
	v_mov_b32_e32 v0, v113
	v_mov_b32_e32 v1, v113
	v_mov_b32_e32 v2, v113
	v_mov_b32_e32 v3, v113
	v_mov_b32_e32 v4, v113
	v_mov_b32_e32 v5, v113
	v_mov_b32_e32 v6, v113
	v_mov_b32_e32 v7, v113
	v_mov_b32_e32 v8, v113
	v_mov_b32_e32 v9, v113
	v_mov_b32_e32 v10, v113
	v_mov_b32_e32 v11, v113
	v_mov_b32_e32 v12, v113
	v_mov_b32_e32 v13, v113
	v_mov_b64_e32 v[30:31], v[14:15]
	v_ashrrev_i32_e32 v149, 6, v144
	v_lshl_add_u64 v[110:111], s[34:35], 0, v[112:113]
	v_lshlrev_b32_e32 v151, 2, v141
	s_or_b32 s15, s14, 1
	s_sub_i32 s14, s14, s32
	s_sub_i32 s15, s15, s32
	v_mov_b32_e32 v97, v98
	v_mov_b32_e32 v99, v98
	v_add_u32_e32 v153, 64, v146
	v_or_b32_e32 v154, 64, v114
	v_add_u32_e32 v155, 64, v145
	v_mov_b32_e32 v157, 0xff800000
	v_mov_b32_e32 v156, 0
	s_mov_b32 s16, s20
	v_mov_b64_e32 v[28:29], v[12:13]
	v_mov_b64_e32 v[26:27], v[10:11]
	v_mov_b64_e32 v[24:25], v[8:9]
	v_mov_b64_e32 v[22:23], v[6:7]
	v_mov_b64_e32 v[20:21], v[4:5]
	v_mov_b64_e32 v[18:19], v[2:3]
	v_mov_b64_e32 v[16:17], v[0:1]
	s_waitcnt lgkmcnt(0)
	s_barrier

; __device__ __forceinline__ int get_bid() { int b = blockIdx.x; asm volatile("" : "+s"(b)); return b; }
; __device__ void run_phase(const Params& p, int ph, char* smem) {
;     ...
;     } else if (s == 1) {
;         for (int it = get_bid(); it < 32; it += gridDim.x) cumsum_item(p, it, smem);
.LBB0_156:
	s_and_b64 vcc, exec, s[0:1]
	s_cbranch_vccz .LBB0_285
	v_readlane_b32 s36, v165, 4
	v_readlane_b32 s37, v165, 5
	v_readlane_b32 s40, v165, 2
	v_readlane_b32 s41, v165, 3
	v_readlane_b32 s42, v167, 36
	s_sub_u32 s36, s36, 0x1a8
	s_subb_u32 s37, s37, 0
	s_load_dwordx2 s[38:39], s[36:37], 0xd8
	s_load_dword s45, s[36:37], 0x1a8
	v_lshrrev_b32_e32 v0, 6, v126
	v_lshlrev_b32_e32 v1, 4, v130
	v_mov_b32_e32 v2, 0
	v_readfirstlane_b32 s44, v0
	v_mov_b32_e32 v3, 0
	s_lshl_b32 s46, s2, 2
	s_add_i32 s44, s44, s46
	s_movk_i32 s43, 0x7fff
	s_waitcnt lgkmcnt(0)
	s_lshl_b32 s45, s45, 2
.Lnorm_loop:
	s_min_i32 s46, s44, s43
	s_mul_i32 s46, s46, 0x1410
	s_add_u32 s48, s38, s46
	s_addc_u32 s49, s39, 0
	global_load_dwordx4 v[4:7], v1, s[48:49]
	global_load_dwordx4 v[8:11], v1, s[48:49] offset:1024
	s_add_i32 s47, s44, s45
	s_min_i32 s46, s47, s43
	s_mul_i32 s46, s46, 0x1410
	s_add_u32 s50, s38, s46
	s_addc_u32 s51, s39, 0
	global_load_dwordx4 v[12:15], v1, s[50:51]
	global_load_dwordx4 v[16:19], v1, s[50:51] offset:1024
	s_add_i32 s47, s47, s45
	s_min_i32 s46, s47, s43
	s_mul_i32 s46, s46, 0x1410
	s_add_u32 s36, s38, s46
	s_addc_u32 s37, s39, 0
	global_load_dwordx4 v[20:23], v1, s[36:37]
	global_load_dwordx4 v[24:27], v1, s[36:37] offset:1024
	s_add_i32 s47, s47, s45
	s_min_i32 s46, s47, s43
	s_mul_i32 s46, s46, 0x1410
	s_add_u32 s48, s38, s46
	s_addc_u32 s49, s39, 0
	global_load_dwordx4 v[28:31], v1, s[48:49]
	global_load_dwordx4 v[32:35], v1, s[48:49] offset:1024
	s_add_i32 s44, s47, s45
	s_waitcnt vmcnt(0)
	v_lshlrev_b32_e32 v38, 16, v4
	v_and_b32_e32 v39, 0xffff0000, v4
	v_mul_f32_e32 v36, v38, v38
	v_fmac_f32_e32 v36, v39, v39
	v_lshlrev_b32_e32 v38, 16, v5
	v_and_b32_e32 v39, 0xffff0000, v5
	v_fmac_f32_e32 v36, v38, v38
	v_fmac_f32_e32 v36, v39, v39
	v_lshlrev_b32_e32 v38, 16, v6
	v_and_b32_e32 v39, 0xffff0000, v6
	v_fmac_f32_e32 v36, v38, v38
	v_fmac_f32_e32 v36, v39, v39
	v_lshlrev_b32_e32 v38, 16, v7
	v_and_b32_e32 v39, 0xffff0000, v7
	v_fmac_f32_e32 v36, v38, v38
	v_fmac_f32_e32 v36, v39, v39
	s_nop 1
	v_add_f32_dpp v36, v36, v36 quad_perm:[1,0,3,2] row_mask:0xf bank_mask:0xf
	s_nop 1
	v_add_f32_dpp v36, v36, v36 quad_perm:[2,3,0,1] row_mask:0xf bank_mask:0xf
	s_nop 1
	v_add_f32_dpp v36, v36, v36 row_half_mirror row_mask:0xf bank_mask:0xf
	v_lshlrev_b32_e32 v40, 16, v8
	v_and_b32_e32 v41, 0xffff0000, v8
	v_mul_f32_e32 v37, v40, v40
	v_fmac_f32_e32 v37, v41, v41
	v_lshlrev_b32_e32 v40, 16, v9
	v_and_b32_e32 v41, 0xffff0000, v9
	v_fmac_f32_e32 v37, v40, v40
	v_fmac_f32_e32 v37, v41, v41
	v_lshlrev_b32_e32 v40, 16, v10
	v_and_b32_e32 v41, 0xffff0000, v10
	v_fmac_f32_e32 v37, v40, v40
	v_fmac_f32_e32 v37, v41, v41
	v_lshlrev_b32_e32 v40, 16, v11
	v_and_b32_e32 v41, 0xffff0000, v11
	v_fmac_f32_e32 v37, v40, v40
	v_fmac_f32_e32 v37, v41, v41
	s_nop 1
	v_add_f32_dpp v37, v37, v37 quad_perm:[1,0,3,2] row_mask:0xf bank_mask:0xf
	s_nop 1
	v_add_f32_dpp v37, v37, v37 quad_perm:[2,3,0,1] row_mask:0xf bank_mask:0xf
	s_nop 1
	v_add_f32_dpp v37, v37, v37 row_half_mirror row_mask:0xf bank_mask:0xf
	v_max_f32_e32 v2, v2, v36
	v_max_f32_e32 v3, v3, v37
	v_lshlrev_b32_e32 v38, 16, v12
	v_and_b32_e32 v39, 0xffff0000, v12
	v_mul_f32_e32 v36, v38, v38
	v_fmac_f32_e32 v36, v39, v39
	v_lshlrev_b32_e32 v38, 16, v13
	v_and_b32_e32 v39, 0xffff0000, v13
	v_fmac_f32_e32 v36, v38, v38
	v_fmac_f32_e32 v36, v39, v39
	v_lshlrev_b32_e32 v38, 16, v14
	v_and_b32_e32 v39, 0xffff0000, v14
	v_fmac_f32_e32 v36, v38, v38
	v_fmac_f32_e32 v36, v39, v39
	v_lshlrev_b32_e32 v38, 16, v15
	v_and_b32_e32 v39, 0xffff0000, v15
	v_fmac_f32_e32 v36, v38, v38
	v_fmac_f32_e32 v36, v39, v39
	s_nop 1
	v_add_f32_dpp v36, v36, v36 quad_perm:[1,0,3,2] row_mask:0xf bank_mask:0xf
	s_nop 1
	v_add_f32_dpp v36, v36, v36 quad_perm:[2,3,0,1] row_mask:0xf bank_mask:0xf
	s_nop 1
	v_add_f32_dpp v36, v36, v36 row_half_mirror row_mask:0xf bank_mask:0xf
	v_lshlrev_b32_e32 v40, 16, v16
	v_and_b32_e32 v41, 0xffff0000, v16
	v_mul_f32_e32 v37, v40, v40
	v_fmac_f32_e32 v37, v41, v41
	v_lshlrev_b32_e32 v40, 16, v17
	v_and_b32_e32 v41, 0xffff0000, v17
	v_fmac_f32_e32 v37, v40, v40
	v_fmac_f32_e32 v37, v41, v41
	v_lshlrev_b32_e32 v40, 16, v18
	v_and_b32_e32 v41, 0xffff0000, v18
	v_fmac_f32_e32 v37, v40, v40
	v_fmac_f32_e32 v37, v41, v41
	v_lshlrev_b32_e32 v40, 16, v19
	v_and_b32_e32 v41, 0xffff0000, v19
	v_fmac_f32_e32 v37, v40, v40
	v_fmac_f32_e32 v37, v41, v41
	s_nop 1
	v_add_f32_dpp v37, v37, v37 quad_perm:[1,0,3,2] row_mask:0xf bank_mask:0xf
; __device__ __forceinline__ int get_bid() { int b = blockIdx.x; asm volatile("" : "+s"(b)); return b; }
; __device__ void run_phase(const Params& p, int ph, char* smem) {
;     ...
;     } else if (s == 1) {
;         for (int it = get_bid(); it < 32; it += gridDim.x) cumsum_item(p, it, smem);
	s_nop 1
	v_add_f32_dpp v37, v37, v37 quad_perm:[2,3,0,1] row_mask:0xf bank_mask:0xf
	s_nop 1
	v_add_f32_dpp v37, v37, v37 row_half_mirror row_mask:0xf bank_mask:0xf
	v_max_f32_e32 v2, v2, v36
	v_max_f32_e32 v3, v3, v37
	v_lshlrev_b32_e32 v38, 16, v20
	v_and_b32_e32 v39, 0xffff0000, v20
	v_mul_f32_e32 v36, v38, v38
	v_fmac_f32_e32 v36, v39, v39
	v_lshlrev_b32_e32 v38, 16, v21
	v_and_b32_e32 v39, 0xffff0000, v21
	v_fmac_f32_e32 v36, v38, v38
	v_fmac_f32_e32 v36, v39, v39
	v_lshlrev_b32_e32 v38, 16, v22
	v_and_b32_e32 v39, 0xffff0000, v22
	v_fmac_f32_e32 v36, v38, v38
	v_fmac_f32_e32 v36, v39, v39
	v_lshlrev_b32_e32 v38, 16, v23
	v_and_b32_e32 v39, 0xffff0000, v23
	v_fmac_f32_e32 v36, v38, v38
	v_fmac_f32_e32 v36, v39, v39
	s_nop 1
	v_add_f32_dpp v36, v36, v36 quad_perm:[1,0,3,2] row_mask:0xf bank_mask:0xf
	s_nop 1
	v_add_f32_dpp v36, v36, v36 quad_perm:[2,3,0,1] row_mask:0xf bank_mask:0xf
	s_nop 1
	v_add_f32_dpp v36, v36, v36 row_half_mirror row_mask:0xf bank_mask:0xf
	v_lshlrev_b32_e32 v40, 16, v24
	v_and_b32_e32 v41, 0xffff0000, v24
	v_mul_f32_e32 v37, v40, v40
	v_fmac_f32_e32 v37, v41, v41
	v_lshlrev_b32_e32 v40, 16, v25
	v_and_b32_e32 v41, 0xffff0000, v25
	v_fmac_f32_e32 v37, v40, v40
	v_fmac_f32_e32 v37, v41, v41
	v_lshlrev_b32_e32 v40, 16, v26
	v_and_b32_e32 v41, 0xffff0000, v26
	v_fmac_f32_e32 v37, v40, v40
	v_fmac_f32_e32 v37, v41, v41
	v_lshlrev_b32_e32 v40, 16, v27
	v_and_b32_e32 v41, 0xffff0000, v27
	v_fmac_f32_e32 v37, v40, v40
	v_fmac_f32_e32 v37, v41, v41
	s_nop 1
	v_add_f32_dpp v37, v37, v37 quad_perm:[1,0,3,2] row_mask:0xf bank_mask:0xf
	s_nop 1
	v_add_f32_dpp v37, v37, v37 quad_perm:[2,3,0,1] row_mask:0xf bank_mask:0xf
	s_nop 1
	v_add_f32_dpp v37, v37, v37 row_half_mirror row_mask:0xf bank_mask:0xf
	v_max_f32_e32 v2, v2, v36
	v_max_f32_e32 v3, v3, v37
	v_lshlrev_b32_e32 v38, 16, v28
	v_and_b32_e32 v39, 0xffff0000, v28
	v_mul_f32_e32 v36, v38, v38
	v_fmac_f32_e32 v36, v39, v39
	v_lshlrev_b32_e32 v38, 16, v29
	v_and_b32_e32 v39, 0xffff0000, v29
	v_fmac_f32_e32 v36, v38, v38
	v_fmac_f32_e32 v36, v39, v39
	v_lshlrev_b32_e32 v38, 16, v30
	v_and_b32_e32 v39, 0xffff0000, v30
	v_fmac_f32_e32 v36, v38, v38
	v_fmac_f32_e32 v36, v39, v39
	v_lshlrev_b32_e32 v38, 16, v31
	v_and_b32_e32 v39, 0xffff0000, v31
	v_fmac_f32_e32 v36, v38, v38
	v_fmac_f32_e32 v36, v39, v39
	s_nop 1
	v_add_f32_dpp v36, v36, v36 quad_perm:[1,0,3,2] row_mask:0xf bank_mask:0xf
	s_nop 1
	v_add_f32_dpp v36, v36, v36 quad_perm:[2,3,0,1] row_mask:0xf bank_mask:0xf
	s_nop 1
	v_add_f32_dpp v36, v36, v36 row_half_mirror row_mask:0xf bank_mask:0xf
	v_lshlrev_b32_e32 v40, 16, v32
	v_and_b32_e32 v41, 0xffff0000, v32
	v_mul_f32_e32 v37, v40, v40
	v_fmac_f32_e32 v37, v41, v41
	v_lshlrev_b32_e32 v40, 16, v33
	v_and_b32_e32 v41, 0xffff0000, v33
	v_fmac_f32_e32 v37, v40, v40
	v_fmac_f32_e32 v37, v41, v41
	v_lshlrev_b32_e32 v40, 16, v34
	v_and_b32_e32 v41, 0xffff0000, v34
	v_fmac_f32_e32 v37, v40, v40
	v_fmac_f32_e32 v37, v41, v41
	v_lshlrev_b32_e32 v40, 16, v35
	v_and_b32_e32 v41, 0xffff0000, v35
	v_fmac_f32_e32 v37, v40, v40
	v_fmac_f32_e32 v37, v41, v41
	s_nop 1
	v_add_f32_dpp v37, v37, v37 quad_perm:[1,0,3,2] row_mask:0xf bank_mask:0xf
	s_nop 1
	v_add_f32_dpp v37, v37, v37 quad_perm:[2,3,0,1] row_mask:0xf bank_mask:0xf
	s_nop 1
	v_add_f32_dpp v37, v37, v37 row_half_mirror row_mask:0xf bank_mask:0xf
	v_max_f32_e32 v2, v2, v36
	v_max_f32_e32 v3, v3, v37
	s_cmp_lt_i32 s44, 0x8000
	s_cbranch_scc1 .Lnorm_loop
	v_lshrrev_b32_e32 v4, 3, v130
	v_lshlrev_b32_e32 v4, 2, v4
	s_mul_i32 s46, s42, 0xc00
	s_and_b32 s47, s2, 7
	s_lshl_b32 s47, s47, 7
	s_add_i32 s46, s46, s47
	s_add_i32 s46, s46, 32
	v_add_u32_e32 v4, s46, v4
	v_and_b32_e32 v5, 7, v130
	v_cmp_eq_u32_e32 vcc, 0, v5
	s_and_saveexec_b64 s[46:47], vcc
	global_atomic_umax v4, v2, s[40:41]
	global_atomic_umax v4, v3, s[40:41] offset:1024
	s_or_b64 exec, exec, s[46:47]
	s_mov_b32 s0, s2
	v_readlane_b32 s36, v165, 26
	s_cmp_gt_i32 s0, 31
	v_readlane_b32 s48, v165, 38
	v_readlane_b32 s49, v165, 39
	v_readlane_b32 s37, v165, 27
	v_readlane_b32 s38, v165, 28
	v_readlane_b32 s39, v165, 29
	v_readlane_b32 s40, v165, 30
	v_readlane_b32 s41, v165, 31
	v_readlane_b32 s42, v165, 32
	v_readlane_b32 s43, v165, 33
	v_readlane_b32 s44, v165, 34
	v_readlane_b32 s45, v165, 35
	v_readlane_b32 s46, v165, 36
	v_readlane_b32 s47, v165, 37
	v_readlane_b32 s50, v165, 40
	v_readlane_b32 s51, v165, 41
	s_cbranch_scc0 .LBB0_190
